# attention: next tile's row maximum interleaved with the last four PV MFMAs off the diagonal; diagonal tiles keep mask-then-max out of line
# speedup vs baseline: 1.0040x; 1.0040x over previous
; __device__ __forceinline__ float max3f(float a, float b, float c) { return __builtin_fmaxf(__builtin_fmaxf(a, b), c); }
; __device__ __forceinline__ float rowmax(const f32x16& p0, const f32x16& p1) {
;     float a = max3f(p0[0], p0[1], p1[0]), b = max3f(p0[2], p0[3], p1[1]); a = max3f(a, p1[2], p1[3]);
; #pragma unroll
;     for (int r = 4; r < 16; r += 4) { a = max3f(a, p0[r], p0[r + 1]); b = max3f(b, p0[r + 2], p0[r + 3]); a = max3f(a, p1[r], p1[r + 1]); b = max3f(b, p1[r + 2], p1[r + 3]); }
;     const float m = __builtin_fmaxf(a, b);
;     auto rr = __builtin_amdgcn_permlane32_swap(__float_as_uint(m), __float_as_uint(m), false, false);
;     return __builtin_fmaxf(__uint_as_float(rr[0]), __uint_as_float(rr[1]));
; }
.Lat_u1x_nodma:
	v_lshl_add_u64 v[126:127], v[126:127], 0, s[34:35]
	v_lshl_add_u64 v[14:15], v[14:15], 0, s[20:21]
	v_lshl_add_u64 v[124:125], v[124:125], 0, s[34:35]
	v_exp_f32_e32 v58, v58
	v_exp_f32_e32 v59, v59
	v_add_f32_e32 v157, v157, v58
	v_add_f32_e32 v157, v157, v59
	v_cvt_pk_bf16_f32 v53, v58, v59
	s_nop 1
	v_mfma_f32_32x32x16_bf16 v[16:31], v[200:203], v[68:71], v[16:31]
	v_exp_f32_e32 v60, v60
	v_exp_f32_e32 v61, v61
	v_add_f32_e32 v156, v156, v60
	v_add_f32_e32 v156, v156, v61
	v_cvt_pk_bf16_f32 v54, v60, v61
	s_nop 1
	v_mfma_f32_32x32x16_bf16 v[32:47], v[230:233], v[68:71], v[32:47]
	v_exp_f32_e32 v62, v62
	v_exp_f32_e32 v63, v63
	v_add_f32_e32 v157, v157, v62
	v_add_f32_e32 v157, v157, v63
	v_cvt_pk_bf16_f32 v55, v62, v63
	s_nop 1
	s_cmp_lt_u32 s52, s87
	s_cbranch_scc0 .Lat_u1x_dg
	v_mfma_f32_32x32x16_bf16 v[16:31], v[204:207], v[48:51], v[16:31]
	v_max3_f32 v129, v238, v239, v240
	v_max3_f32 v131, v241, v242, v243
	v_max3_f32 v129, v129, v244, v245
	v_max3_f32 v131, v131, v246, v247
	v_max3_f32 v129, v129, v248, v249
	v_mfma_f32_32x32x16_bf16 v[32:47], v[234:237], v[48:51], v[32:47]
	v_max3_f32 v131, v131, v250, v251
	v_max3_f32 v129, v129, v252, v253
	v_max3_f32 v131, v131, v180, v181
	v_add_f32_e32 v156, v156, v157
	v_max3_f32 v129, v129, v182, v183
	v_mfma_f32_32x32x16_bf16 v[16:31], v[208:211], v[52:55], v[16:31]
	v_max3_f32 v131, v131, v184, v185
	v_max3_f32 v129, v129, v186, v187
	v_max3_f32 v131, v131, v188, v189
	v_max3_f32 v129, v129, v190, v191
	v_max3_f32 v131, v131, v192, v193
	v_mfma_f32_32x32x16_bf16 v[32:47], v[164:167], v[52:55], v[32:47]
	v_max3_f32 v129, v129, v194, v195
	v_max_f32_e32 v129, v129, v131
	v_add_f32_e32 v128, v128, v156
.Lat_u1x_rm:
	v_cmp_lt_f32_e32 vcc, 0x41000000, v129
	s_cbranch_vccnz .Lat_u1x_rare

; __device__ __forceinline__ float max3f(float a, float b, float c) { return __builtin_fmaxf(__builtin_fmaxf(a, b), c); }
; __device__ __forceinline__ float rowmax(const f32x16& p0, const f32x16& p1) {
;     float a = max3f(p0[0], p0[1], p1[0]), b = max3f(p0[2], p0[3], p1[1]); a = max3f(a, p1[2], p1[3]);
; #pragma unroll
;     for (int r = 4; r < 16; r += 4) { a = max3f(a, p0[r], p0[r + 1]); b = max3f(b, p0[r + 2], p0[r + 3]); a = max3f(a, p1[r], p1[r + 1]); b = max3f(b, p1[r + 2], p1[r + 3]); }
;     const float m = __builtin_fmaxf(a, b);
;     auto rr = __builtin_amdgcn_permlane32_swap(__float_as_uint(m), __float_as_uint(m), false, false);
;     return __builtin_fmaxf(__uint_as_float(rr[0]), __uint_as_float(rr[1]));
; }
.Lat_u1y_nodma:
	v_lshl_add_u64 v[126:127], v[126:127], 0, s[34:35]
	v_lshl_add_u64 v[14:15], v[14:15], 0, s[20:21]
	v_lshl_add_u64 v[124:125], v[124:125], 0, s[34:35]
	v_exp_f32_e32 v190, v190
	v_exp_f32_e32 v191, v191
	v_add_f32_e32 v157, v157, v190
	v_add_f32_e32 v157, v157, v191
	v_cvt_pk_bf16_f32 v185, v190, v191
	s_nop 1
	v_mfma_f32_32x32x16_bf16 v[16:31], v[200:203], v[242:245], v[16:31]
	v_exp_f32_e32 v192, v192
	v_exp_f32_e32 v193, v193
	v_add_f32_e32 v156, v156, v192
	v_add_f32_e32 v156, v156, v193
	v_cvt_pk_bf16_f32 v186, v192, v193
	s_nop 1
	v_mfma_f32_32x32x16_bf16 v[32:47], v[230:233], v[242:245], v[32:47]
	v_exp_f32_e32 v194, v194
	v_exp_f32_e32 v195, v195
	v_add_f32_e32 v157, v157, v194
	v_add_f32_e32 v157, v157, v195
	v_cvt_pk_bf16_f32 v187, v194, v195
	s_nop 1
	s_cmp_lt_u32 s52, s87
	s_cbranch_scc0 .Lat_u1y_dg
	v_mfma_f32_32x32x16_bf16 v[16:31], v[204:207], v[180:183], v[16:31]
	v_max3_f32 v129, v64, v65, v66
	v_max3_f32 v131, v67, v68, v69
	v_max3_f32 v129, v129, v70, v71
	v_max3_f32 v131, v131, v72, v73
	v_max3_f32 v129, v129, v74, v75
	v_mfma_f32_32x32x16_bf16 v[32:47], v[234:237], v[180:183], v[32:47]
	v_max3_f32 v131, v131, v76, v77
	v_max3_f32 v129, v129, v78, v79
	v_max3_f32 v131, v131, v48, v49
	v_add_f32_e32 v156, v156, v157
	v_max3_f32 v129, v129, v50, v51
	v_mfma_f32_32x32x16_bf16 v[16:31], v[208:211], v[184:187], v[16:31]
	v_max3_f32 v131, v131, v52, v53
	v_max3_f32 v129, v129, v54, v55
	v_max3_f32 v131, v131, v56, v57
	v_max3_f32 v129, v129, v58, v59
	v_max3_f32 v131, v131, v60, v61
	v_mfma_f32_32x32x16_bf16 v[32:47], v[164:167], v[184:187], v[32:47]
	v_max3_f32 v129, v129, v62, v63
	v_max_f32_e32 v129, v129, v131
	v_add_f32_e32 v128, v128, v156

; __device__ __forceinline__ void cmask(f32x16& p0, f32x16& p1, int jb, int qrel, int hi) {
;     const float NEG = -INFINITY; const int kb = 64 * jb + 4 * hi;
; #pragma unroll
;     for (int r = 0; r < 16; ++r) { const int kv = kb + (r & 3) + 8 * (r >> 2); if (kv > qrel) p0[r] = NEG; if (kv + 32 > qrel) p1[r] = NEG; }
; }
; __device__ __forceinline__ void glds16(const void* gsrc, unsigned lds_dst) { unsigned keep;
;     asm volatile("s_mov_b32 %0, m0\n\ts_mov_b32 m0, %2\n\ts_nop 0\n\tglobal_load_lds_dwordx4 %1, off\n\ts_mov_b32 m0, %0" : "=&s"(keep) : "v"(gsrc), "s"(lds_dst) : "memory"); }
; __device__ __forceinline__ float max3f(float a, float b, float c) { return __builtin_fmaxf(__builtin_fmaxf(a, b), c); }
; __device__ __forceinline__ float rowmax(const f32x16& p0, const f32x16& p1) {
;     float a = max3f(p0[0], p0[1], p1[0]), b = max3f(p0[2], p0[3], p1[1]); a = max3f(a, p1[2], p1[3]);
; #pragma unroll
;     for (int r = 4; r < 16; r += 4) { a = max3f(a, p0[r], p0[r + 1]); b = max3f(b, p0[r + 2], p0[r + 3]); a = max3f(a, p1[r], p1[r + 1]); b = max3f(b, p1[r + 2], p1[r + 3]); }
;     const float m = __builtin_fmaxf(a, b);
;     auto rr = __builtin_amdgcn_permlane32_swap(__float_as_uint(m), __float_as_uint(m), false, false);
;     return __builtin_fmaxf(__uint_as_float(rr[0]), __uint_as_float(rr[1]));
; }
.Lat_u1x_dg:
	v_mfma_f32_32x32x16_bf16 v[16:31], v[204:207], v[48:51], v[16:31]
	v_mfma_f32_32x32x16_bf16 v[32:47], v[234:237], v[48:51], v[32:47]
	v_mfma_f32_32x32x16_bf16 v[16:31], v[208:211], v[52:55], v[16:31]
	v_mfma_f32_32x32x16_bf16 v[32:47], v[164:167], v[52:55], v[32:47]
	v_add_f32_e32 v156, v156, v157
	v_add_f32_e32 v128, v128, v156
	s_sub_i32 s4, s52, s87
	s_lshl_b32 s4, s4, 6
	s_nop 7
	s_nop 7
	v_lshl_add_u32 v147, v141, 2, s4
	v_sub_u32_e32 v147, v145, v147
	v_cmp_gt_i32_e32 vcc, 0, v147
	s_nop 1
	v_cndmask_b32_e32 v238, v238, v220, vcc
	v_cmp_gt_i32_e32 vcc, 1, v147
	s_nop 1
	v_cndmask_b32_e32 v239, v239, v220, vcc
	v_cmp_gt_i32_e32 vcc, 2, v147
	s_nop 1
	v_cndmask_b32_e32 v240, v240, v220, vcc
	v_cmp_gt_i32_e32 vcc, 3, v147
	s_nop 1
	v_cndmask_b32_e32 v241, v241, v220, vcc
	v_cmp_gt_i32_e32 vcc, 8, v147
	s_nop 1
	v_cndmask_b32_e32 v242, v242, v220, vcc
	v_cmp_gt_i32_e32 vcc, 9, v147
	s_nop 1
	v_cndmask_b32_e32 v243, v243, v220, vcc
	v_cmp_gt_i32_e32 vcc, 10, v147
	s_nop 1
	v_cndmask_b32_e32 v244, v244, v220, vcc
	v_cmp_gt_i32_e32 vcc, 11, v147
	s_nop 1
	v_cndmask_b32_e32 v245, v245, v220, vcc
	v_cmp_gt_i32_e32 vcc, 16, v147
	s_nop 1
	v_cndmask_b32_e32 v246, v246, v220, vcc
	v_cmp_gt_i32_e32 vcc, 17, v147
	s_nop 1
	v_cndmask_b32_e32 v247, v247, v220, vcc
	v_cmp_gt_i32_e32 vcc, 18, v147
	s_nop 1
	v_cndmask_b32_e32 v248, v248, v220, vcc
	v_cmp_gt_i32_e32 vcc, 19, v147
	s_nop 1
	v_cndmask_b32_e32 v249, v249, v220, vcc
	v_cmp_gt_i32_e32 vcc, 24, v147
	s_nop 1
	v_cndmask_b32_e32 v250, v250, v220, vcc
	v_cmp_gt_i32_e32 vcc, 25, v147
	s_nop 1
	v_cndmask_b32_e32 v251, v251, v220, vcc
	v_cmp_gt_i32_e32 vcc, 26, v147
	s_nop 1
	v_cndmask_b32_e32 v252, v252, v220, vcc
	v_cmp_gt_i32_e32 vcc, 27, v147
	s_nop 1
	v_cndmask_b32_e32 v253, v253, v220, vcc
	v_cmp_gt_i32_e32 vcc, 32, v147
	s_nop 1
	v_cndmask_b32_e32 v180, v180, v220, vcc
	v_cmp_gt_i32_e32 vcc, 33, v147
	s_nop 1
	v_cndmask_b32_e32 v181, v181, v220, vcc
	v_cmp_gt_i32_e32 vcc, 34, v147
	s_nop 1
	v_cndmask_b32_e32 v182, v182, v220, vcc
	v_cmp_gt_i32_e32 vcc, 35, v147
	s_nop 1
	v_cndmask_b32_e32 v183, v183, v220, vcc
	v_cmp_gt_i32_e32 vcc, 40, v147
	s_nop 1
	v_cndmask_b32_e32 v184, v184, v220, vcc
	v_cmp_gt_i32_e32 vcc, 41, v147
	s_nop 1
	v_cndmask_b32_e32 v185, v185, v220, vcc
	v_cmp_gt_i32_e32 vcc, 42, v147
	s_nop 1
	v_cndmask_b32_e32 v186, v186, v220, vcc
	v_cmp_gt_i32_e32 vcc, 43, v147
	s_nop 1
	v_cndmask_b32_e32 v187, v187, v220, vcc
	v_cmp_gt_i32_e32 vcc, 48, v147
	s_nop 1
	v_cndmask_b32_e32 v188, v188, v220, vcc
	v_cmp_gt_i32_e32 vcc, 49, v147
	s_nop 1
	v_cndmask_b32_e32 v189, v189, v220, vcc
	v_cmp_gt_i32_e32 vcc, 50, v147
	s_nop 1
	v_cndmask_b32_e32 v190, v190, v220, vcc
	v_cmp_gt_i32_e32 vcc, 51, v147
	s_nop 1
	v_cndmask_b32_e32 v191, v191, v220, vcc
	v_cmp_gt_i32_e32 vcc, 56, v147
	s_nop 1
	v_cndmask_b32_e32 v192, v192, v220, vcc
	v_cmp_gt_i32_e32 vcc, 57, v147
	s_nop 1
	v_cndmask_b32_e32 v193, v193, v220, vcc
	v_cmp_gt_i32_e32 vcc, 58, v147
	s_nop 1
	v_cndmask_b32_e32 v194, v194, v220, vcc
	v_cmp_gt_i32_e32 vcc, 59, v147
	s_nop 1
	v_cndmask_b32_e32 v195, v195, v220, vcc
	v_max3_f32 v129, v238, v239, v240
	v_max3_f32 v131, v241, v242, v243
	v_max3_f32 v129, v129, v244, v245
	v_max3_f32 v131, v131, v246, v247
	v_max3_f32 v129, v129, v248, v249
	v_max3_f32 v131, v131, v250, v251
	v_max3_f32 v129, v129, v252, v253
	v_max3_f32 v131, v131, v180, v181
	v_max3_f32 v129, v129, v182, v183
	v_max3_f32 v131, v131, v184, v185
	v_max3_f32 v129, v129, v186, v187
	v_max3_f32 v131, v131, v188, v189
	v_max3_f32 v129, v129, v190, v191
	v_max3_f32 v131, v131, v192, v193
	v_max3_f32 v129, v129, v194, v195
	v_max_f32_e32 v129, v129, v131
	s_branch .Lat_u1x_rm
; __device__ __forceinline__ void cmask(f32x16& p0, f32x16& p1, int jb, int qrel, int hi) {
;     const float NEG = -INFINITY; const int kb = 64 * jb + 4 * hi;
; #pragma unroll
;     for (int r = 0; r < 16; ++r) { const int kv = kb + (r & 3) + 8 * (r >> 2); if (kv > qrel) p0[r] = NEG; if (kv + 32 > qrel) p1[r] = NEG; }
; }
; __device__ __forceinline__ void glds16(const void* gsrc, unsigned lds_dst) { unsigned keep;
;     asm volatile("s_mov_b32 %0, m0\n\ts_mov_b32 m0, %2\n\ts_nop 0\n\tglobal_load_lds_dwordx4 %1, off\n\ts_mov_b32 m0, %0" : "=&s"(keep) : "v"(gsrc), "s"(lds_dst) : "memory"); }
; __device__ __forceinline__ float max3f(float a, float b, float c) { return __builtin_fmaxf(__builtin_fmaxf(a, b), c); }
; __device__ __forceinline__ float rowmax(const f32x16& p0, const f32x16& p1) {
;     float a = max3f(p0[0], p0[1], p1[0]), b = max3f(p0[2], p0[3], p1[1]); a = max3f(a, p1[2], p1[3]);
; #pragma unroll
;     for (int r = 4; r < 16; r += 4) { a = max3f(a, p0[r], p0[r + 1]); b = max3f(b, p0[r + 2], p0[r + 3]); a = max3f(a, p1[r], p1[r + 1]); b = max3f(b, p1[r + 2], p1[r + 3]); }
;     const float m = __builtin_fmaxf(a, b);
;     auto rr = __builtin_amdgcn_permlane32_swap(__float_as_uint(m), __float_as_uint(m), false, false);
;     return __builtin_fmaxf(__uint_as_float(rr[0]), __uint_as_float(rr[1]));
; }
.Lat_u1y_dg:
	v_mfma_f32_32x32x16_bf16 v[16:31], v[204:207], v[180:183], v[16:31]
	v_mfma_f32_32x32x16_bf16 v[32:47], v[234:237], v[180:183], v[32:47]
	v_mfma_f32_32x32x16_bf16 v[16:31], v[208:211], v[184:187], v[16:31]
	v_mfma_f32_32x32x16_bf16 v[32:47], v[164:167], v[184:187], v[32:47]
	v_add_f32_e32 v156, v156, v157
	v_add_f32_e32 v128, v128, v156
	s_sub_i32 s4, s52, s87
	s_lshl_b32 s4, s4, 6
	s_nop 7
	s_nop 7
	v_lshl_add_u32 v147, v141, 2, s4
	v_sub_u32_e32 v147, v145, v147
	v_cmp_gt_i32_e32 vcc, 0, v147
	s_nop 1
	v_cndmask_b32_e32 v64, v64, v220, vcc
	v_cmp_gt_i32_e32 vcc, 1, v147
	s_nop 1
	v_cndmask_b32_e32 v65, v65, v220, vcc
	v_cmp_gt_i32_e32 vcc, 2, v147
	s_nop 1
	v_cndmask_b32_e32 v66, v66, v220, vcc
	v_cmp_gt_i32_e32 vcc, 3, v147
	s_nop 1
	v_cndmask_b32_e32 v67, v67, v220, vcc
	v_cmp_gt_i32_e32 vcc, 8, v147
	s_nop 1
	v_cndmask_b32_e32 v68, v68, v220, vcc
	v_cmp_gt_i32_e32 vcc, 9, v147
	s_nop 1
	v_cndmask_b32_e32 v69, v69, v220, vcc
	v_cmp_gt_i32_e32 vcc, 10, v147
	s_nop 1
	v_cndmask_b32_e32 v70, v70, v220, vcc
	v_cmp_gt_i32_e32 vcc, 11, v147
	s_nop 1
	v_cndmask_b32_e32 v71, v71, v220, vcc
	v_cmp_gt_i32_e32 vcc, 16, v147
	s_nop 1
	v_cndmask_b32_e32 v72, v72, v220, vcc
	v_cmp_gt_i32_e32 vcc, 17, v147
	s_nop 1
	v_cndmask_b32_e32 v73, v73, v220, vcc
	v_cmp_gt_i32_e32 vcc, 18, v147
	s_nop 1
	v_cndmask_b32_e32 v74, v74, v220, vcc
	v_cmp_gt_i32_e32 vcc, 19, v147
	s_nop 1
	v_cndmask_b32_e32 v75, v75, v220, vcc
	v_cmp_gt_i32_e32 vcc, 24, v147
	s_nop 1
	v_cndmask_b32_e32 v76, v76, v220, vcc
	v_cmp_gt_i32_e32 vcc, 25, v147
	s_nop 1
	v_cndmask_b32_e32 v77, v77, v220, vcc
	v_cmp_gt_i32_e32 vcc, 26, v147
	s_nop 1
	v_cndmask_b32_e32 v78, v78, v220, vcc
	v_cmp_gt_i32_e32 vcc, 27, v147
	s_nop 1
	v_cndmask_b32_e32 v79, v79, v220, vcc
	v_cmp_gt_i32_e32 vcc, 32, v147
	s_nop 1
	v_cndmask_b32_e32 v48, v48, v220, vcc
	v_cmp_gt_i32_e32 vcc, 33, v147
	s_nop 1
	v_cndmask_b32_e32 v49, v49, v220, vcc
	v_cmp_gt_i32_e32 vcc, 34, v147
	s_nop 1
	v_cndmask_b32_e32 v50, v50, v220, vcc
	v_cmp_gt_i32_e32 vcc, 35, v147
	s_nop 1
	v_cndmask_b32_e32 v51, v51, v220, vcc
	v_cmp_gt_i32_e32 vcc, 40, v147
	s_nop 1
	v_cndmask_b32_e32 v52, v52, v220, vcc
	v_cmp_gt_i32_e32 vcc, 41, v147
	s_nop 1
	v_cndmask_b32_e32 v53, v53, v220, vcc
	v_cmp_gt_i32_e32 vcc, 42, v147
	s_nop 1
	v_cndmask_b32_e32 v54, v54, v220, vcc
	v_cmp_gt_i32_e32 vcc, 43, v147
	s_nop 1
	v_cndmask_b32_e32 v55, v55, v220, vcc
	v_cmp_gt_i32_e32 vcc, 48, v147
	s_nop 1
	v_cndmask_b32_e32 v56, v56, v220, vcc
	v_cmp_gt_i32_e32 vcc, 49, v147
	s_nop 1
	v_cndmask_b32_e32 v57, v57, v220, vcc
	v_cmp_gt_i32_e32 vcc, 50, v147
	s_nop 1
	v_cndmask_b32_e32 v58, v58, v220, vcc
	v_cmp_gt_i32_e32 vcc, 51, v147
	s_nop 1
	v_cndmask_b32_e32 v59, v59, v220, vcc
	v_cmp_gt_i32_e32 vcc, 56, v147
	s_nop 1
	v_cndmask_b32_e32 v60, v60, v220, vcc
	v_cmp_gt_i32_e32 vcc, 57, v147
	s_nop 1
	v_cndmask_b32_e32 v61, v61, v220, vcc
	v_cmp_gt_i32_e32 vcc, 58, v147
	s_nop 1
	v_cndmask_b32_e32 v62, v62, v220, vcc
	v_cmp_gt_i32_e32 vcc, 59, v147
	s_nop 1
	v_cndmask_b32_e32 v63, v63, v220, vcc
	v_max3_f32 v129, v64, v65, v66
	v_max3_f32 v131, v67, v68, v69
	v_max3_f32 v129, v129, v70, v71
	v_max3_f32 v131, v131, v72, v73
	v_max3_f32 v129, v129, v74, v75
	v_max3_f32 v131, v131, v76, v77
	v_max3_f32 v129, v129, v78, v79
	v_max3_f32 v131, v131, v48, v49
	v_max3_f32 v129, v129, v50, v51
	v_max3_f32 v131, v131, v52, v53
	v_max3_f32 v129, v129, v54, v55
	v_max3_f32 v131, v131, v56, v57
	v_max3_f32 v129, v129, v58, v59
	v_max3_f32 v131, v131, v60, v61
	v_max3_f32 v129, v129, v62, v63
	v_max_f32_e32 v129, v129, v131
	s_branch .Lat_u1y_rm

; __device__ __forceinline__ float max3f(float a, float b, float c) { return __builtin_fmaxf(__builtin_fmaxf(a, b), c); }
; __device__ __forceinline__ float rowmax(const f32x16& p0, const f32x16& p1) {
;     float a = max3f(p0[0], p0[1], p1[0]), b = max3f(p0[2], p0[3], p1[1]); a = max3f(a, p1[2], p1[3]);
; #pragma unroll
;     for (int r = 4; r < 16; r += 4) { a = max3f(a, p0[r], p0[r + 1]); b = max3f(b, p0[r + 2], p0[r + 3]); a = max3f(a, p1[r], p1[r + 1]); b = max3f(b, p1[r + 2], p1[r + 3]); }
;     const float m = __builtin_fmaxf(a, b);
;     auto rr = __builtin_amdgcn_permlane32_swap(__float_as_uint(m), __float_as_uint(m), false, false);
;     return __builtin_fmaxf(__uint_as_float(rr[0]), __uint_as_float(rr[1]));
; }
.Lat_u2x_nodma:
	v_lshl_add_u64 v[126:127], v[126:127], 0, s[34:35]
	v_lshl_add_u64 v[122:123], v[122:123], 0, s[20:21]
	v_lshl_add_u64 v[124:125], v[124:125], 0, s[34:35]
	v_exp_f32_e32 v44, v44
	v_exp_f32_e32 v45, v45
	v_add_f32_e32 v157, v157, v44
	v_add_f32_e32 v157, v157, v45
	v_cvt_pk_bf16_f32 v39, v44, v45
	s_nop 1
	v_mfma_f32_32x32x16_bf16 v[18:33], v[200:203], v[54:57], v[18:33]
	v_exp_f32_e32 v46, v46
	v_exp_f32_e32 v47, v47
	v_add_f32_e32 v156, v156, v46
	v_add_f32_e32 v156, v156, v47
	v_cvt_pk_bf16_f32 v40, v46, v47
	s_nop 1
	v_mfma_f32_32x32x16_bf16 v[2:17], v[230:233], v[54:57], v[2:17]
	v_exp_f32_e32 v48, v48
	v_exp_f32_e32 v49, v49
	v_add_f32_e32 v157, v157, v48
	v_add_f32_e32 v157, v157, v49
	v_cvt_pk_bf16_f32 v41, v48, v49
	s_nop 1
	s_cmp_lt_u32 s62, s91
	s_cbranch_scc0 .Lat_u2x_dg
	v_mfma_f32_32x32x16_bf16 v[18:33], v[204:207], v[34:37], v[18:33]
	v_max3_f32 v131, v238, v239, v240
	v_max3_f32 v132, v241, v242, v243
	v_max3_f32 v131, v131, v244, v245
	v_max3_f32 v132, v132, v246, v247
	v_max3_f32 v131, v131, v248, v249
	v_mfma_f32_32x32x16_bf16 v[2:17], v[234:237], v[34:37], v[2:17]
	v_max3_f32 v132, v132, v250, v251
	v_max3_f32 v131, v131, v252, v253
	v_max3_f32 v132, v132, v180, v181
	v_add_f32_e32 v156, v156, v157
	v_max3_f32 v131, v131, v182, v183
	v_mfma_f32_32x32x16_bf16 v[18:33], v[208:211], v[38:41], v[18:33]
	v_max3_f32 v132, v132, v184, v185
	v_max3_f32 v131, v131, v186, v187
	v_max3_f32 v132, v132, v188, v189
	v_max3_f32 v131, v131, v190, v191
	v_max3_f32 v132, v132, v192, v193
	v_mfma_f32_32x32x16_bf16 v[2:17], v[164:167], v[38:41], v[2:17]
	v_max3_f32 v131, v131, v194, v195
	v_max_f32_e32 v131, v131, v132
	v_add_f32_e32 v128, v128, v156
.Lat_u2x_rm:
	v_cmp_lt_f32_e32 vcc, 0x41000000, v131
	s_cbranch_vccnz .Lat_u2x_rare

; __device__ __forceinline__ float max3f(float a, float b, float c) { return __builtin_fmaxf(__builtin_fmaxf(a, b), c); }
; __device__ __forceinline__ float rowmax(const f32x16& p0, const f32x16& p1) {
;     float a = max3f(p0[0], p0[1], p1[0]), b = max3f(p0[2], p0[3], p1[1]); a = max3f(a, p1[2], p1[3]);
; #pragma unroll
;     for (int r = 4; r < 16; r += 4) { a = max3f(a, p0[r], p0[r + 1]); b = max3f(b, p0[r + 2], p0[r + 3]); a = max3f(a, p1[r], p1[r + 1]); b = max3f(b, p1[r + 2], p1[r + 3]); }
;     const float m = __builtin_fmaxf(a, b);
;     auto rr = __builtin_amdgcn_permlane32_swap(__float_as_uint(m), __float_as_uint(m), false, false);
;     return __builtin_fmaxf(__uint_as_float(rr[0]), __uint_as_float(rr[1]));
; }
.Lat_u2y_nodma:
	v_lshl_add_u64 v[126:127], v[126:127], 0, s[34:35]
	v_lshl_add_u64 v[122:123], v[122:123], 0, s[20:21]
	v_lshl_add_u64 v[124:125], v[124:125], 0, s[34:35]
	v_exp_f32_e32 v190, v190
	v_exp_f32_e32 v191, v191
	v_add_f32_e32 v157, v157, v190
	v_add_f32_e32 v157, v157, v191
	v_cvt_pk_bf16_f32 v185, v190, v191
	s_nop 1
	v_mfma_f32_32x32x16_bf16 v[18:33], v[200:203], v[242:245], v[18:33]
	v_exp_f32_e32 v192, v192
	v_exp_f32_e32 v193, v193
	v_add_f32_e32 v156, v156, v192
	v_add_f32_e32 v156, v156, v193
	v_cvt_pk_bf16_f32 v186, v192, v193
	s_nop 1
	v_mfma_f32_32x32x16_bf16 v[2:17], v[230:233], v[242:245], v[2:17]
	v_exp_f32_e32 v194, v194
	v_exp_f32_e32 v195, v195
	v_add_f32_e32 v157, v157, v194
	v_add_f32_e32 v157, v157, v195
	v_cvt_pk_bf16_f32 v187, v194, v195
	s_nop 1
	s_cmp_lt_u32 s62, s91
	s_cbranch_scc0 .Lat_u2y_dg
	v_mfma_f32_32x32x16_bf16 v[18:33], v[204:207], v[180:183], v[18:33]
	v_max3_f32 v131, v50, v51, v52
	v_max3_f32 v132, v53, v54, v55
	v_max3_f32 v131, v131, v56, v57
	v_max3_f32 v132, v132, v58, v59
	v_max3_f32 v131, v131, v60, v61
	v_mfma_f32_32x32x16_bf16 v[2:17], v[234:237], v[180:183], v[2:17]
	v_max3_f32 v132, v132, v62, v63
	v_max3_f32 v131, v131, v64, v65
	v_max3_f32 v132, v132, v34, v35
	v_add_f32_e32 v156, v156, v157
	v_max3_f32 v131, v131, v36, v37
	v_mfma_f32_32x32x16_bf16 v[18:33], v[208:211], v[184:187], v[18:33]
	v_max3_f32 v132, v132, v38, v39
	v_max3_f32 v131, v131, v40, v41
	v_max3_f32 v132, v132, v42, v43
	v_max3_f32 v131, v131, v44, v45
	v_max3_f32 v132, v132, v46, v47
	v_mfma_f32_32x32x16_bf16 v[2:17], v[164:167], v[184:187], v[2:17]
	v_max3_f32 v131, v131, v48, v49
	v_max_f32_e32 v131, v131, v132
	v_add_f32_e32 v128, v128, v156

; __device__ __forceinline__ void cmask(f32x16& p0, f32x16& p1, int jb, int qrel, int hi) {
;     const float NEG = -INFINITY; const int kb = 64 * jb + 4 * hi;
; #pragma unroll
;     for (int r = 0; r < 16; ++r) { const int kv = kb + (r & 3) + 8 * (r >> 2); if (kv > qrel) p0[r] = NEG; if (kv + 32 > qrel) p1[r] = NEG; }
; }
; __device__ __forceinline__ void glds16(const void* gsrc, unsigned lds_dst) { unsigned keep;
;     asm volatile("s_mov_b32 %0, m0\n\ts_mov_b32 m0, %2\n\ts_nop 0\n\tglobal_load_lds_dwordx4 %1, off\n\ts_mov_b32 m0, %0" : "=&s"(keep) : "v"(gsrc), "s"(lds_dst) : "memory"); }
; __device__ __forceinline__ float max3f(float a, float b, float c) { return __builtin_fmaxf(__builtin_fmaxf(a, b), c); }
; __device__ __forceinline__ float rowmax(const f32x16& p0, const f32x16& p1) {
;     float a = max3f(p0[0], p0[1], p1[0]), b = max3f(p0[2], p0[3], p1[1]); a = max3f(a, p1[2], p1[3]);
; #pragma unroll
;     for (int r = 4; r < 16; r += 4) { a = max3f(a, p0[r], p0[r + 1]); b = max3f(b, p0[r + 2], p0[r + 3]); a = max3f(a, p1[r], p1[r + 1]); b = max3f(b, p1[r + 2], p1[r + 3]); }
;     const float m = __builtin_fmaxf(a, b);
;     auto rr = __builtin_amdgcn_permlane32_swap(__float_as_uint(m), __float_as_uint(m), false, false);
;     return __builtin_fmaxf(__uint_as_float(rr[0]), __uint_as_float(rr[1]));
; }
.Lat_u2x_dg:
	v_mfma_f32_32x32x16_bf16 v[18:33], v[204:207], v[34:37], v[18:33]
	v_mfma_f32_32x32x16_bf16 v[2:17], v[234:237], v[34:37], v[2:17]
	v_mfma_f32_32x32x16_bf16 v[18:33], v[208:211], v[38:41], v[18:33]
	v_mfma_f32_32x32x16_bf16 v[2:17], v[164:167], v[38:41], v[2:17]
	v_add_f32_e32 v156, v156, v157
	v_add_f32_e32 v128, v128, v156
	s_sub_i32 s4, s62, s91
	s_lshl_b32 s4, s4, 6
	s_nop 7
	s_nop 7
	v_lshl_add_u32 v133, v142, 2, s4
	v_sub_u32_e32 v133, v145, v133
	v_cmp_gt_i32_e32 vcc, 0, v133
	s_nop 1
	v_cndmask_b32_e32 v238, v238, v220, vcc
	v_cmp_gt_i32_e32 vcc, 1, v133
	s_nop 1
	v_cndmask_b32_e32 v239, v239, v220, vcc
	v_cmp_gt_i32_e32 vcc, 2, v133
	s_nop 1
	v_cndmask_b32_e32 v240, v240, v220, vcc
	v_cmp_gt_i32_e32 vcc, 3, v133
	s_nop 1
	v_cndmask_b32_e32 v241, v241, v220, vcc
	v_cmp_gt_i32_e32 vcc, 8, v133
	s_nop 1
	v_cndmask_b32_e32 v242, v242, v220, vcc
	v_cmp_gt_i32_e32 vcc, 9, v133
	s_nop 1
	v_cndmask_b32_e32 v243, v243, v220, vcc
	v_cmp_gt_i32_e32 vcc, 10, v133
	s_nop 1
	v_cndmask_b32_e32 v244, v244, v220, vcc
	v_cmp_gt_i32_e32 vcc, 11, v133
	s_nop 1
	v_cndmask_b32_e32 v245, v245, v220, vcc
	v_cmp_gt_i32_e32 vcc, 16, v133
	s_nop 1
	v_cndmask_b32_e32 v246, v246, v220, vcc
	v_cmp_gt_i32_e32 vcc, 17, v133
	s_nop 1
	v_cndmask_b32_e32 v247, v247, v220, vcc
	v_cmp_gt_i32_e32 vcc, 18, v133
	s_nop 1
	v_cndmask_b32_e32 v248, v248, v220, vcc
	v_cmp_gt_i32_e32 vcc, 19, v133
	s_nop 1
	v_cndmask_b32_e32 v249, v249, v220, vcc
	v_cmp_gt_i32_e32 vcc, 24, v133
	s_nop 1
	v_cndmask_b32_e32 v250, v250, v220, vcc
	v_cmp_gt_i32_e32 vcc, 25, v133
	s_nop 1
	v_cndmask_b32_e32 v251, v251, v220, vcc
	v_cmp_gt_i32_e32 vcc, 26, v133
	s_nop 1
	v_cndmask_b32_e32 v252, v252, v220, vcc
	v_cmp_gt_i32_e32 vcc, 27, v133
	s_nop 1
	v_cndmask_b32_e32 v253, v253, v220, vcc
	v_cmp_gt_i32_e32 vcc, 32, v133
	s_nop 1
	v_cndmask_b32_e32 v180, v180, v220, vcc
	v_cmp_gt_i32_e32 vcc, 33, v133
	s_nop 1
	v_cndmask_b32_e32 v181, v181, v220, vcc
	v_cmp_gt_i32_e32 vcc, 34, v133
	s_nop 1
	v_cndmask_b32_e32 v182, v182, v220, vcc
	v_cmp_gt_i32_e32 vcc, 35, v133
	s_nop 1
	v_cndmask_b32_e32 v183, v183, v220, vcc
	v_cmp_gt_i32_e32 vcc, 40, v133
	s_nop 1
	v_cndmask_b32_e32 v184, v184, v220, vcc
	v_cmp_gt_i32_e32 vcc, 41, v133
	s_nop 1
	v_cndmask_b32_e32 v185, v185, v220, vcc
	v_cmp_gt_i32_e32 vcc, 42, v133
	s_nop 1
	v_cndmask_b32_e32 v186, v186, v220, vcc
	v_cmp_gt_i32_e32 vcc, 43, v133
	s_nop 1
	v_cndmask_b32_e32 v187, v187, v220, vcc
	v_cmp_gt_i32_e32 vcc, 48, v133
	s_nop 1
	v_cndmask_b32_e32 v188, v188, v220, vcc
	v_cmp_gt_i32_e32 vcc, 49, v133
	s_nop 1
	v_cndmask_b32_e32 v189, v189, v220, vcc
	v_cmp_gt_i32_e32 vcc, 50, v133
	s_nop 1
	v_cndmask_b32_e32 v190, v190, v220, vcc
	v_cmp_gt_i32_e32 vcc, 51, v133
	s_nop 1
	v_cndmask_b32_e32 v191, v191, v220, vcc
	v_cmp_gt_i32_e32 vcc, 56, v133
	s_nop 1
	v_cndmask_b32_e32 v192, v192, v220, vcc
	v_cmp_gt_i32_e32 vcc, 57, v133
	s_nop 1
	v_cndmask_b32_e32 v193, v193, v220, vcc
	v_cmp_gt_i32_e32 vcc, 58, v133
	s_nop 1
	v_cndmask_b32_e32 v194, v194, v220, vcc
	v_cmp_gt_i32_e32 vcc, 59, v133
	s_nop 1
	v_cndmask_b32_e32 v195, v195, v220, vcc
	v_max3_f32 v131, v238, v239, v240
	v_max3_f32 v132, v241, v242, v243
	v_max3_f32 v131, v131, v244, v245
	v_max3_f32 v132, v132, v246, v247
	v_max3_f32 v131, v131, v248, v249
	v_max3_f32 v132, v132, v250, v251
	v_max3_f32 v131, v131, v252, v253
	v_max3_f32 v132, v132, v180, v181
	v_max3_f32 v131, v131, v182, v183
	v_max3_f32 v132, v132, v184, v185
	v_max3_f32 v131, v131, v186, v187
	v_max3_f32 v132, v132, v188, v189
	v_max3_f32 v131, v131, v190, v191
	v_max3_f32 v132, v132, v192, v193
	v_max3_f32 v131, v131, v194, v195
	v_max_f32_e32 v131, v131, v132
	s_branch .Lat_u2x_rm
; __device__ __forceinline__ void cmask(f32x16& p0, f32x16& p1, int jb, int qrel, int hi) {
;     const float NEG = -INFINITY; const int kb = 64 * jb + 4 * hi;
; #pragma unroll
;     for (int r = 0; r < 16; ++r) { const int kv = kb + (r & 3) + 8 * (r >> 2); if (kv > qrel) p0[r] = NEG; if (kv + 32 > qrel) p1[r] = NEG; }
; }
; __device__ __forceinline__ void glds16(const void* gsrc, unsigned lds_dst) { unsigned keep;
;     asm volatile("s_mov_b32 %0, m0\n\ts_mov_b32 m0, %2\n\ts_nop 0\n\tglobal_load_lds_dwordx4 %1, off\n\ts_mov_b32 m0, %0" : "=&s"(keep) : "v"(gsrc), "s"(lds_dst) : "memory"); }
; __device__ __forceinline__ float max3f(float a, float b, float c) { return __builtin_fmaxf(__builtin_fmaxf(a, b), c); }
; __device__ __forceinline__ float rowmax(const f32x16& p0, const f32x16& p1) {
;     float a = max3f(p0[0], p0[1], p1[0]), b = max3f(p0[2], p0[3], p1[1]); a = max3f(a, p1[2], p1[3]);
; #pragma unroll
;     for (int r = 4; r < 16; r += 4) { a = max3f(a, p0[r], p0[r + 1]); b = max3f(b, p0[r + 2], p0[r + 3]); a = max3f(a, p1[r], p1[r + 1]); b = max3f(b, p1[r + 2], p1[r + 3]); }
;     const float m = __builtin_fmaxf(a, b);
;     auto rr = __builtin_amdgcn_permlane32_swap(__float_as_uint(m), __float_as_uint(m), false, false);
;     return __builtin_fmaxf(__uint_as_float(rr[0]), __uint_as_float(rr[1]));
; }
.Lat_u2y_dg:
	v_mfma_f32_32x32x16_bf16 v[18:33], v[204:207], v[180:183], v[18:33]
	v_mfma_f32_32x32x16_bf16 v[2:17], v[234:237], v[180:183], v[2:17]
	v_mfma_f32_32x32x16_bf16 v[18:33], v[208:211], v[184:187], v[18:33]
	v_mfma_f32_32x32x16_bf16 v[2:17], v[164:167], v[184:187], v[2:17]
	v_add_f32_e32 v156, v156, v157
	v_add_f32_e32 v128, v128, v156
	s_sub_i32 s4, s62, s91
	s_lshl_b32 s4, s4, 6
	s_nop 7
	s_nop 7
	v_lshl_add_u32 v133, v142, 2, s4
	v_sub_u32_e32 v133, v145, v133
	v_cmp_gt_i32_e32 vcc, 0, v133
	s_nop 1
	v_cndmask_b32_e32 v50, v50, v220, vcc
	v_cmp_gt_i32_e32 vcc, 1, v133
	s_nop 1
	v_cndmask_b32_e32 v51, v51, v220, vcc
	v_cmp_gt_i32_e32 vcc, 2, v133
	s_nop 1
	v_cndmask_b32_e32 v52, v52, v220, vcc
	v_cmp_gt_i32_e32 vcc, 3, v133
	s_nop 1
	v_cndmask_b32_e32 v53, v53, v220, vcc
	v_cmp_gt_i32_e32 vcc, 8, v133
	s_nop 1
	v_cndmask_b32_e32 v54, v54, v220, vcc
	v_cmp_gt_i32_e32 vcc, 9, v133
	s_nop 1
	v_cndmask_b32_e32 v55, v55, v220, vcc
	v_cmp_gt_i32_e32 vcc, 10, v133
	s_nop 1
	v_cndmask_b32_e32 v56, v56, v220, vcc
	v_cmp_gt_i32_e32 vcc, 11, v133
	s_nop 1
	v_cndmask_b32_e32 v57, v57, v220, vcc
	v_cmp_gt_i32_e32 vcc, 16, v133
	s_nop 1
	v_cndmask_b32_e32 v58, v58, v220, vcc
	v_cmp_gt_i32_e32 vcc, 17, v133
	s_nop 1
	v_cndmask_b32_e32 v59, v59, v220, vcc
	v_cmp_gt_i32_e32 vcc, 18, v133
	s_nop 1
	v_cndmask_b32_e32 v60, v60, v220, vcc
	v_cmp_gt_i32_e32 vcc, 19, v133
	s_nop 1
	v_cndmask_b32_e32 v61, v61, v220, vcc
	v_cmp_gt_i32_e32 vcc, 24, v133
	s_nop 1
	v_cndmask_b32_e32 v62, v62, v220, vcc
	v_cmp_gt_i32_e32 vcc, 25, v133
	s_nop 1
	v_cndmask_b32_e32 v63, v63, v220, vcc
	v_cmp_gt_i32_e32 vcc, 26, v133
	s_nop 1
	v_cndmask_b32_e32 v64, v64, v220, vcc
	v_cmp_gt_i32_e32 vcc, 27, v133
	s_nop 1
	v_cndmask_b32_e32 v65, v65, v220, vcc
	v_cmp_gt_i32_e32 vcc, 32, v133
	s_nop 1
	v_cndmask_b32_e32 v34, v34, v220, vcc
	v_cmp_gt_i32_e32 vcc, 33, v133
	s_nop 1
	v_cndmask_b32_e32 v35, v35, v220, vcc
	v_cmp_gt_i32_e32 vcc, 34, v133
	s_nop 1
	v_cndmask_b32_e32 v36, v36, v220, vcc
	v_cmp_gt_i32_e32 vcc, 35, v133
	s_nop 1
	v_cndmask_b32_e32 v37, v37, v220, vcc
	v_cmp_gt_i32_e32 vcc, 40, v133
	s_nop 1
	v_cndmask_b32_e32 v38, v38, v220, vcc
	v_cmp_gt_i32_e32 vcc, 41, v133
	s_nop 1
	v_cndmask_b32_e32 v39, v39, v220, vcc
	v_cmp_gt_i32_e32 vcc, 42, v133
	s_nop 1
	v_cndmask_b32_e32 v40, v40, v220, vcc
	v_cmp_gt_i32_e32 vcc, 43, v133
	s_nop 1
	v_cndmask_b32_e32 v41, v41, v220, vcc
	v_cmp_gt_i32_e32 vcc, 48, v133
	s_nop 1
	v_cndmask_b32_e32 v42, v42, v220, vcc
	v_cmp_gt_i32_e32 vcc, 49, v133
	s_nop 1
	v_cndmask_b32_e32 v43, v43, v220, vcc
	v_cmp_gt_i32_e32 vcc, 50, v133
	s_nop 1
	v_cndmask_b32_e32 v44, v44, v220, vcc
	v_cmp_gt_i32_e32 vcc, 51, v133
	s_nop 1
	v_cndmask_b32_e32 v45, v45, v220, vcc
	v_cmp_gt_i32_e32 vcc, 56, v133
	s_nop 1
	v_cndmask_b32_e32 v46, v46, v220, vcc
	v_cmp_gt_i32_e32 vcc, 57, v133
	s_nop 1
	v_cndmask_b32_e32 v47, v47, v220, vcc
	v_cmp_gt_i32_e32 vcc, 58, v133
	s_nop 1
	v_cndmask_b32_e32 v48, v48, v220, vcc
	v_cmp_gt_i32_e32 vcc, 59, v133
	s_nop 1
	v_cndmask_b32_e32 v49, v49, v220, vcc
	v_max3_f32 v131, v50, v51, v52
	v_max3_f32 v132, v53, v54, v55
	v_max3_f32 v131, v131, v56, v57
	v_max3_f32 v132, v132, v58, v59
	v_max3_f32 v131, v131, v60, v61
	v_max3_f32 v132, v132, v62, v63
	v_max3_f32 v131, v131, v64, v65
	v_max3_f32 v132, v132, v34, v35
	v_max3_f32 v131, v131, v36, v37
	v_max3_f32 v132, v132, v38, v39
	v_max3_f32 v131, v131, v40, v41
	v_max3_f32 v132, v132, v42, v43
	v_max3_f32 v131, v131, v44, v45
	v_max3_f32 v132, v132, v46, v47
	v_max3_f32 v131, v131, v48, v49
	v_max_f32_e32 v131, v131, v132
	s_branch .Lat_u2y_rm
